# v37 + static priority 1 for waves 0-3 through the GEMM phases (flipped to waves 4-7 inside FoX)
# speedup vs baseline: 1.0039x; 1.0005x over previous
;     __host__ __device__ bool next(int i, Unit& u) const {
;         const long L = (long)i * G + c; if (L >= nwg) return false;
;         int wgid = (int)L; { const int q = nwg / NXCD, r = nwg % NXCD, xcd = wgid % NXCD, off = wgid / NXCD; wgid = (xcd < r ? xcd * (q + 1) : r * (q + 1) + (xcd - r) * q) + off; }
;         const int nig = WGM * nN, gid = wgid / nig, fm = gid * WGM, gsz = (nM - fm) < WGM ? (nM - fm) : WGM;
;         u.pm = fm + ((wgid % nig) % gsz); u.pn = (wgid % nig) / gsz; return true;
; template <class GEO, class Epi>
; __device__ __forceinline__ void gemm_phase(LAS unsigned char* lds, const Gemm g, const StaticOrder& S, const Epi& E) {
;     ...
;     Unit cur, nxt; int ui = 0;
;     if (!S.next(0, cur)) return;
.LBB0_154:
	s_or_b64 exec, exec, s[4:5]
	v_readfirstlane_b32 s100, v208
	s_lshr_b32 s100, s100, 8
	s_cmp_lg_u32 s100, 0
	s_cbranch_scc0 .Lgp_p1_lo
	s_setprio 0
	s_branch .Lgp_p1_done
.Lgp_p1_lo:
	s_setprio 1
.Lgp_p1_done:
	s_cmpk_lt_i32 s2, 0x680
	s_cselect_b64 s[4:5], -1, 0
	v_mov_b32_e32 v8, v208
	s_waitcnt lgkmcnt(0)
	s_barrier
	s_and_b64 vcc, exec, s[4:5]
	v_readfirstlane_b32 s6, v8
	s_cbranch_vccz .LBB0_156
	s_ashr_i32 s3, s2, 31
	s_lshr_b32 s3, s3, 29
	s_add_i32 s3, s2, s3
	s_ashr_i32 s7, s3, 3
	s_and_b32 s3, s3, -8
	s_sub_i32 s3, s2, s3
	s_cmp_lt_i32 s3, 0
	s_movk_i32 s8, 0xd1
	s_cselect_b32 s8, s8, 0xd0
	s_mul_i32 s3, s3, s8
	s_add_i32 s3, s3, s7
	s_mul_hi_i32 s7, s3, 0x4ec4ec4f
	s_lshr_b32 s8, s7, 31
	s_ashr_i32 s7, s7, 4
	s_add_i32 s7, s7, s8
	s_lshl_b32 s8, s7, 2
	s_mul_i32 s7, s7, 52
	s_sub_i32 s3, s3, s7
	s_bfe_i32 s7, s3, 0x80000
	s_bfe_u32 s7, s7, 0x2000d
	s_add_i32 s7, s3, s7
	s_bfe_i32 s9, s7, 0x80000
	s_and_b32 s7, s7, 0xfc
	s_sub_i32 s3, s3, s7
	s_sext_i32_i16 s9, s9
	s_sext_i32_i8 s3, s3
	s_add_i32 s18, s8, s3
	s_ashr_i32 s12, s9, 2

; DI int get_tid() { int t = threadIdx.x; asm volatile("" : "+v"(t)); return t; }
; DI void fox_bh_setup(int bh, const Params& p, LAS unsigned char* lds) {
;     ...
;     if (wid == 0) { const float v0 = ct[2 * lane], v1 = ct[2 * lane + 1], s = v0 + v1; float incl = s;
; #pragma unroll
;         for (int o = 1; o < 64; o <<= 1) { const float t = __shfl_up(incl, o); if (lane >= o) incl += t; }
; __global__ void __launch_bounds__(512, 2) fwd_megakernel(Params p) {
;     ...
;     { const int tl = get_tid() & 63; float gq = fabsf(p.fox_q_g[tl]), gk = fabsf(p.fox_k_g[tl]);
; #pragma unroll
;       for (int o = 1; o < 64; o <<= 1) { gq = fmaxf(gq, __shfl_xor(gq, o)); gk = fmaxf(gk, __shfl_xor(gk, o)); }
;       const float bqk = 64.0f * gq * gk * 0.125f * LOG2E * 1.02f, thr2 = 150.0f + bqk;
;       if (G == 256) { const int bh = (bx & 7) * 4 + (bx >> 6), j = (bx >> 3) & 7;
;           fox_bh_setup(bh, p, lds);
;           for (int i = 3; i >= 0; --i) fox_unit(bh, j + 8 * i, p, lds, thr2); }
;       else { for (int u = bx; u < 1024; u += G) { fox_bh_setup(u >> 5, p, lds); fox_unit(u >> 5, u & 31, p, lds, thr2); } } }
.LBB0_436:
	v_mov_b32_e32 v0, v208
	s_waitcnt vmcnt(0)
	s_barrier
	v_readfirstlane_b32 s100, v208
	s_lshr_b32 s100, s100, 8
	s_cmp_lg_u32 s100, 0
	s_cbranch_scc0 .Lgp_fox_lo
	s_setprio 1
	s_branch .Lgp_fox_done
.Lgp_fox_lo:
	s_setprio 0
.Lgp_fox_done:
	v_and_b32_e32 v211, 64, v206
	v_and_b32_e32 v0, 63, v0
	v_lshlrev_b32_e32 v0, 2, v0
	global_load_dword v1, v0, s[26:27]
	s_nop 0
	global_load_dword v0, v0, s[28:29]
	v_xor_b32_e32 v2, 1, v206
	v_add_u32_e32 v8, 64, v211
	v_cmp_lt_i32_e32 vcc, v2, v8
	v_xor_b32_e32 v3, 2, v206
	v_xor_b32_e32 v4, 4, v206
	v_cndmask_b32_e32 v2, v206, v2, vcc
	v_lshlrev_b32_e32 v2, 2, v2
	v_cmp_lt_i32_e32 vcc, v3, v8
	v_xor_b32_e32 v5, 8, v206
	v_xor_b32_e32 v6, 16, v206
	v_cndmask_b32_e32 v3, v206, v3, vcc
	v_lshlrev_b32_e32 v3, 2, v3
	v_cmp_lt_i32_e32 vcc, v4, v8
	v_xor_b32_e32 v7, 32, v206
	v_readlane_b32 s0, v254, 37
	v_cndmask_b32_e32 v4, v206, v4, vcc
	v_lshlrev_b32_e32 v4, 2, v4
	v_cmp_lt_i32_e32 vcc, v5, v8
	s_add_u32 s83, s76, 0x16000000
	v_mov_b32_e32 v207, 0x43160000
	v_readlane_b32 s1, v254, 38
	s_addc_u32 s88, s77, 0
	s_mov_b64 s[20:21], -1
	s_waitcnt vmcnt(1)
	v_and_b32_e32 v9, 0x7fffffff, v1
	s_waitcnt vmcnt(0)
	v_and_b32_e32 v10, 0x7fffffff, v0
	ds_bpermute_b32 v9, v2, v9
	ds_bpermute_b32 v2, v2, v10
	v_max_f32_e64 v1, |v1|, |v1|
	v_max_f32_e64 v0, |v0|, |v0|
	s_waitcnt lgkmcnt(1)
	v_max_f32_e32 v9, v9, v9
	s_waitcnt lgkmcnt(0)
	v_max_f32_e32 v2, v2, v2
	v_max_f32_e32 v1, v1, v9
	v_max_f32_e32 v0, v0, v2
	ds_bpermute_b32 v2, v3, v1
	ds_bpermute_b32 v3, v3, v0
	s_waitcnt lgkmcnt(1)
	v_max_f32_e32 v2, v2, v2
	s_waitcnt lgkmcnt(0)
	v_max_f32_e32 v3, v3, v3
	v_max_f32_e32 v1, v1, v2
	v_max_f32_e32 v0, v0, v3
	ds_bpermute_b32 v2, v4, v1
	ds_bpermute_b32 v3, v4, v0
	v_cndmask_b32_e32 v4, v206, v5, vcc
	v_lshlrev_b32_e32 v4, 2, v4
	v_cmp_lt_i32_e32 vcc, v6, v8
	s_waitcnt lgkmcnt(1)
	v_max_f32_e32 v2, v2, v2
	s_waitcnt lgkmcnt(0)
	v_max_f32_e32 v3, v3, v3
	v_max_f32_e32 v1, v1, v2
	v_max_f32_e32 v0, v0, v3
	ds_bpermute_b32 v2, v4, v1
	ds_bpermute_b32 v3, v4, v0
	v_cndmask_b32_e32 v4, v206, v6, vcc
	v_lshlrev_b32_e32 v209, 2, v4
	v_cmp_lt_i32_e32 vcc, v7, v8
	s_waitcnt lgkmcnt(1)
	v_max_f32_e32 v2, v2, v2
	s_waitcnt lgkmcnt(0)
	v_max_f32_e32 v3, v3, v3
	v_max_f32_e32 v1, v1, v2
	v_max_f32_e32 v0, v0, v3
	ds_bpermute_b32 v2, v209, v1
	ds_bpermute_b32 v3, v209, v0
	v_cndmask_b32_e32 v4, v206, v7, vcc
	v_lshlrev_b32_e32 v210, 2, v4
	s_andn2_b64 vcc, exec, s[0:1]
	s_waitcnt lgkmcnt(1)
	v_max_f32_e32 v2, v2, v2
	s_waitcnt lgkmcnt(0)
	v_max_f32_e32 v3, v3, v3
	v_max_f32_e32 v1, v1, v2
	v_max_f32_e32 v0, v0, v3
	ds_bpermute_b32 v2, v210, v1
	ds_bpermute_b32 v3, v210, v0
	s_waitcnt lgkmcnt(1)
	v_max_f32_e32 v2, v2, v2
	s_waitcnt lgkmcnt(0)
	v_max_f32_e32 v3, v3, v3
	v_max_f32_e32 v1, v1, v2
	v_max_f32_e32 v0, v0, v3
	v_mul_f32_e32 v1, 0x42800000, v1
	v_mul_f32_e32 v0, v0, v1
	v_mul_f32_e32 v0, 0x3e000000, v0
	v_mul_f32_e32 v0, 0x3fb8aa3b, v0
	v_fmac_f32_e32 v207, 0x3f828f5c, v0
	s_cbranch_vccnz .LBB0_502
	s_cmpk_gt_i32 s2, 0x3ff
	s_cbranch_scc1 .LBB0_501
	v_add_u32_e32 v0, -1, v206
	v_cmp_lt_i32_e32 vcc, v0, v211
	s_lshl_b32 s0, s92, 8
	v_mov_b32_e32 v1, 0
	v_cndmask_b32_e32 v0, v0, v206, vcc
	v_lshlrev_b32_e32 v212, 2, v0
	v_add_u32_e32 v0, -2, v206
	v_cmp_lt_i32_e32 vcc, v0, v211
	s_mov_b32 s27, 0
	s_movk_i32 s1, 0x1a00
	v_cndmask_b32_e32 v0, v0, v206, vcc
	v_lshlrev_b32_e32 v213, 2, v0
	v_add_u32_e32 v0, -4, v206
	v_cmp_lt_i32_e32 vcc, v0, v211
	v_mov_b64_e32 v[166:167], s[14:15]
	v_mov_b32_e32 v218, 0x1a00
	v_cndmask_b32_e32 v0, v0, v206, vcc
	v_lshlrev_b32_e32 v214, 2, v0
	v_add_u32_e32 v0, -8, v206
	v_cmp_lt_i32_e32 vcc, v0, v211
	s_add_i32 s4, 0, 0x12a00
	s_add_i32 s5, 0, 0x12400
	v_cndmask_b32_e32 v0, v0, v206, vcc
	v_lshlrev_b32_e32 v215, 2, v0
	v_add_u32_e32 v0, -16, v206
	v_cmp_lt_i32_e32 vcc, v0, v211
	s_add_i32 s6, 0, 0x12000
	s_mov_b32 s7, 0xff800000
	v_cndmask_b32_e32 v0, v0, v206, vcc
	v_lshlrev_b32_e32 v216, 2, v0
	v_subrev_u32_e32 v0, 32, v206
	v_cmp_lt_i32_e32 vcc, v0, v211
	v_mov_b32_e32 v219, 0xff800000
	s_mov_b32 s12, s2
	v_cndmask_b32_e32 v0, v0, v206, vcc
	v_lshlrev_b32_e32 v217, 2, v0
	s_branch .LBB0_440

; __global__ void __launch_bounds__(512, 2) fwd_megakernel(Params p) {
;     ...
;           for (int i = 3; i >= 0; --i) fox_unit(bh, j + 8 * i, p, lds, thr2); }
;       else { for (int u = bx; u < 1024; u += G) { fox_bh_setup(u >> 5, p, lds); fox_unit(u >> 5, u & 31, p, lds, thr2); } } }
.LBB0_566:
	v_readfirstlane_b32 s100, v208
	s_lshr_b32 s100, s100, 8
	s_cmp_lg_u32 s100, 0
	s_cbranch_scc0 .Lgp_foxend_lo
	s_setprio 0
	s_branch .Lgp_foxend_done
